# grid barrier keeps its per-workgroup state (XCD workgroup count, XCD count) in two spare lanes of the SGPR-spill VGPR instead of LDS
# speedup vs baseline: 1.0043x; 1.0043x over previous
; #define LAS __attribute__((address_space(3)))
; __global__ void __launch_bounds__(NTHR, 2) mega(P p, int ph_lo, int ph_hi) {
;     ...
;   __shared__ uint4 xb_words;
;   if (threadIdx.x == 0) xb_words = make_uint4(0u, 0u, 0u, 0u);
;   __syncthreads();
;   XcdBarrier xb; xb.bar = p.bar; xb.x = 0; xb.st = (volatile LAS unsigned*)&xb_words;
;   if (blockIdx.x == 0) { for (int i = threadIdx.x; i < XCD_BAR_WORDS; i += NTHR) p.bar[i] = 0u; }
.LBB0_2:
	s_or_b64 exec, exec, s[2:3]
	s_mov_b32 s2, 0
	s_nop 0
	v_writelane_b32 v229, s2, 55
	v_writelane_b32 v229, s2, 56
	s_nop 0
	s_nop 0
	s_nop 0
	s_nop 0
	s_nop 0
	s_nop 0
	s_nop 0
	s_nop 0
	s_nop 0
	s_mov_b32 s2, 0
	s_nop 0
	v_writelane_b32 v229, s2, 58
	v_writelane_b32 v229, s2, 59
	v_writelane_b32 v229, s2, 60
	s_load_dwordx2 s[82:83], s[0:1], 0x898
	s_load_dwordx2 s[34:35], s[0:1], 0x230
	v_readlane_b32 s2, v230, 0
	s_cmp_lg_u32 s2, 0
	s_waitcnt lgkmcnt(0)
	s_barrier
	s_cbranch_scc0 .LBB0_4
	s_load_dwordx2 s[8:9], s[0:1], 0x890
	s_waitcnt lgkmcnt(0)
	s_cmp_ge_i32 s8, s9
	s_cbranch_scc0 .LBB0_11
	s_getpc_b64 s[98:99]

; __device__ __forceinline__ void xcd_barrier(const XcdBarrier& b) {
;   asm volatile("s_waitcnt vmcnt(0)" ::: "memory");
;   __syncthreads();
;   if (threadIdx.x == 0) {
;     unsigned* bar = b.bar;
;     __builtin_amdgcn_s_waitcnt(0);
;     unsigned nloc = b.st[0], nx = b.st[1];
;     if (nloc == 0u) { xcd_barrier_complete(bar, b.x, nloc, nx); b.st[0] = nloc; b.st[1] = nx; }
.Lxb_hr:
	s_waitcnt vmcnt(0)
	s_barrier
	s_mov_b64 s[6:7], exec
	v_readlane_b32 s8, v230, 3
	v_readlane_b32 s9, v230, 4
	s_and_b64 s[8:9], s[6:7], s[8:9]
	s_mov_b64 exec, s[8:9]
	s_cbranch_execz .LBB0_64
	s_waitcnt vmcnt(0) expcnt(0) lgkmcnt(0)
	v_readlane_b32 s12, v229, 55
	v_readlane_b32 s13, v229, 56
	s_nop 0
	v_mov_b32_e32 v2, s12
	v_mov_b32_e32 v0, s13
	v_cmp_ne_u32_e32 vcc, 0, v2
	s_cbranch_vccnz .LBB0_32
	s_mov_b32 s4, 1
	s_branch .LBB0_20

; __device__ __forceinline__ unsigned xb_ld(unsigned* p)              { return __hip_atomic_load(p, __ATOMIC_RELAXED, __HIP_MEMORY_SCOPE_AGENT); }
; __device__ __forceinline__ void xcd_barrier_complete(unsigned* bar, unsigned x, unsigned& nloc, unsigned& nx) {
;     ...
;     for (unsigned j = 0; j < 16; ++j) { const unsigned c = xb_ld(&bar[XB_XCNT(j)]); sum += c; cnt += (c > 0u) ? 1u : 0u; mine = (j == x) ? c : mine; }
;     if (sum == G) break;
;     __builtin_amdgcn_s_sleep(1);
;     if ((++sp & 255u) == 0u) { if (xb_ld(&bar[XB_TMO])) break; if (sp > XB_SPIN_CAP) { atomicAdd(&bar[XB_TMO], 1u); break; } }
;   }
;   nloc = mine > 0u ? mine : 1u; nx = cnt > 0u ? cnt : 1u;
; }
; __device__ __forceinline__ void xcd_barrier(const XcdBarrier& b) {
;   asm volatile("s_waitcnt vmcnt(0)" ::: "memory");
;   __syncthreads();
;   if (threadIdx.x == 0) {
;     unsigned* bar = b.bar;
;     __builtin_amdgcn_s_waitcnt(0);
;     unsigned nloc = b.st[0], nx = b.st[1];
;     if (nloc == 0u) { xcd_barrier_complete(bar, b.x, nloc, nx); b.st[0] = nloc; b.st[1] = nx; }
.LBB0_31:
	v_readlane_b32 s4, v229, 26
	s_cmp_eq_u32 s4, 0
	s_cselect_b64 vcc, -1, 0
	s_cmp_eq_u32 s4, 1
	v_cndmask_b32_e32 v16, 0, v11, vcc
	s_cselect_b64 vcc, -1, 0
	s_cmp_eq_u32 s4, 2
	v_cndmask_b32_e32 v16, v16, v0, vcc
	s_cselect_b64 vcc, -1, 0
	s_cmp_eq_u32 s4, 3
	v_cndmask_b32_e32 v16, v16, v1, vcc
	s_cselect_b64 vcc, -1, 0
	s_cmp_eq_u32 s4, 4
	v_cndmask_b32_e32 v16, v16, v2, vcc
	s_cselect_b64 vcc, -1, 0
	s_cmp_eq_u32 s4, 5
	v_cndmask_b32_e32 v16, v16, v3, vcc
	s_cselect_b64 vcc, -1, 0
	s_cmp_eq_u32 s4, 6
	v_cndmask_b32_e32 v16, v16, v4, vcc
	s_cselect_b64 vcc, -1, 0
	s_cmp_eq_u32 s4, 7
	v_cndmask_b32_e32 v16, v16, v5, vcc
	s_cselect_b64 vcc, -1, 0
	s_cmp_eq_u32 s4, 8
	v_cndmask_b32_e32 v16, v16, v6, vcc
	s_cselect_b64 vcc, -1, 0
	s_cmp_eq_u32 s4, 9
	v_cndmask_b32_e32 v16, v16, v7, vcc
	s_cselect_b64 vcc, -1, 0
	s_cmp_eq_u32 s4, 10
	v_cndmask_b32_e32 v16, v16, v8, vcc
	s_cselect_b64 vcc, -1, 0
	s_cmp_eq_u32 s4, 11
	v_cndmask_b32_e32 v16, v16, v9, vcc
	s_cselect_b64 vcc, -1, 0
	s_cmp_eq_u32 s4, 12
	v_cndmask_b32_e32 v16, v16, v10, vcc
	s_cselect_b64 vcc, -1, 0
	s_cmp_eq_u32 s4, 13
	v_cndmask_b32_e32 v16, v16, v12, vcc
	s_cselect_b64 vcc, -1, 0
	s_cmp_eq_u32 s4, 14
	v_cndmask_b32_e32 v16, v16, v13, vcc
	s_cselect_b64 vcc, -1, 0
	s_cmp_eq_u32 s4, 15
	v_cndmask_b32_e32 v16, v16, v14, vcc
	s_cselect_b64 vcc, -1, 0
	v_cndmask_b32_e32 v16, v16, v15, vcc
	v_cmp_ne_u32_e32 vcc, 0, v11
	s_nop 1
	v_cndmask_b32_e64 v11, 0, 1, vcc
	v_cmp_ne_u32_e32 vcc, 0, v0
	s_nop 1
	v_addc_co_u32_e32 v0, vcc, 0, v11, vcc
	v_cmp_ne_u32_e32 vcc, 0, v1
	s_nop 1
	v_cndmask_b32_e64 v1, 0, 1, vcc
	v_cmp_ne_u32_e32 vcc, 0, v2
	v_max_u32_e32 v2, 1, v16
	s_nop 0
	v_addc_co_u32_e32 v0, vcc, v0, v1, vcc
	v_cmp_ne_u32_e32 vcc, 0, v3
	s_nop 1
	v_cndmask_b32_e64 v1, 0, 1, vcc
	v_cmp_ne_u32_e32 vcc, 0, v4
	s_nop 1
	v_addc_co_u32_e32 v0, vcc, v0, v1, vcc
	v_cmp_ne_u32_e32 vcc, 0, v5
	s_nop 1
	v_cndmask_b32_e64 v1, 0, 1, vcc
	v_cmp_ne_u32_e32 vcc, 0, v6
	s_nop 1
	v_addc_co_u32_e32 v0, vcc, v0, v1, vcc
	v_cmp_ne_u32_e32 vcc, 0, v7
	s_nop 1
	v_cndmask_b32_e64 v1, 0, 1, vcc
	v_cmp_ne_u32_e32 vcc, 0, v8
	s_nop 1
	v_addc_co_u32_e32 v0, vcc, v0, v1, vcc
	v_cmp_ne_u32_e32 vcc, 0, v9
	s_nop 1
	v_cndmask_b32_e64 v1, 0, 1, vcc
	v_cmp_ne_u32_e32 vcc, 0, v10
	s_nop 1
	v_addc_co_u32_e32 v0, vcc, v0, v1, vcc
	v_cmp_ne_u32_e32 vcc, 0, v12
	s_nop 1
	v_cndmask_b32_e64 v1, 0, 1, vcc
	v_cmp_ne_u32_e32 vcc, 0, v13
	s_nop 1
	v_addc_co_u32_e32 v0, vcc, v0, v1, vcc
	v_cmp_ne_u32_e32 vcc, 0, v14
	s_nop 1
	v_cndmask_b32_e64 v1, 0, 1, vcc
	v_cmp_ne_u32_e32 vcc, 0, v15
	s_nop 1
	v_addc_co_u32_e32 v0, vcc, v0, v1, vcc
	v_max_u32_e32 v0, 1, v0
	v_readfirstlane_b32 s12, v2
	v_readfirstlane_b32 s13, v0
	s_nop 3
	v_writelane_b32 v229, s12, 55
	v_writelane_b32 v229, s13, 56
	v_readlane_b32 s12, v229, 58
	s_nop 3
	s_cmp_eq_u32 s12, 0
	s_cbranch_scc1 .Lxb_ncu0
	v_mov_b32_e32 v8, s12
	global_load_dword v8, v8, s[34:35] sc1
	s_waitcnt vmcnt(0)
	v_readfirstlane_b32 s13, v8
	s_nop 3
	s_lshr_b32 s13, s13, 16
	s_cmp_eq_u32 s13, 2
	s_cselect_b32 s12, s12, 0
	s_cselect_b32 s13, s13, 0
	s_sub_u32 s14, s13, 1
	s_cmp_eq_u32 s13, 0
	s_cselect_b32 s14, 0, s14
	s_nop 0
	v_writelane_b32 v229, s12, 58
	v_writelane_b32 v229, s13, 59
	v_writelane_b32 v229, s14, 60
